# attention K-tile loop restructured: anti-phase wave pairs with one mid-tile barrier, 7-deep V^T fragment prefetch, K fragments prefetched in P.V tail, lag-wave tile staging moved behind QK
# speedup vs baseline: 1.0261x; 1.0261x over previous
.LBB0_227:
	s_lshl_b32 s4, s59, 11
	s_and_b32 s5, s4, 0x1000000
	s_lshl_b32 s4, s36, 4
	s_and_b32 s28, s4, 0x700
	v_lshl_or_b32 v96, v148, 1, s28
	v_or_b32_e32 v96, s5, v96
	v_mov_b32_e32 v97, v209
	s_lshl_b32 s21, s21, 9
	s_mov_b32 s65, 2
	s_add_i32 s66, s8, 2
	s_mov_b32 s4, 1
	v_lshl_add_u64 v[174:175], v[170:171], 0, v[96:97]
	v_subrev_u32_e32 v204, s21, v194
	s_add_i32 s33, s61, s8
	s_mov_b32 s87, 0
	s_movk_i32 s68, 0xff00
	s_waitcnt lgkmcnt(0)
	s_barrier
	s_and_b64 vcc, exec, s[16:17]
	s_cbranch_vccnz .LBB0_228
	s_cmp_lt_i32 s9, 1
	s_cbranch_scc1 .LBB0_228
	s_movk_i32 s5, 0x4400
	v_add_u32_e32 v205, s5, v192
	ds_read_b128 v[96:99], v205 offset:8704
	ds_read_b128 v[100:103], v205 offset:8736
	ds_read_b128 v[104:107], v205 offset:8768
	ds_read_b128 v[108:111], v205 offset:8800
	ds_read_b128 v[176:179], v205
	ds_read_b128 v[180:183], v205 offset:32
	ds_read_b128 v[184:187], v205 offset:64
	ds_read_b128 v[188:191], v205 offset:96
	s_waitcnt lgkmcnt(7)
	v_mfma_f32_32x32x16_bf16 v[80:95], v[96:99], v[112:115], v[64:79]
	s_waitcnt lgkmcnt(6)
	v_mfma_f32_32x32x16_bf16 v[80:95], v[100:103], v[116:119], v[80:95]
	s_waitcnt lgkmcnt(5)
	v_mfma_f32_32x32x16_bf16 v[80:95], v[104:107], v[120:123], v[80:95]
	s_waitcnt lgkmcnt(4)
	v_mfma_f32_32x32x16_bf16 v[80:95], v[108:111], v[124:127], v[80:95]
	s_waitcnt lgkmcnt(3)
	v_mfma_f32_32x32x16_bf16 v[96:111], v[176:179], v[112:115], v[64:79]
	s_waitcnt lgkmcnt(2)
	v_mfma_f32_32x32x16_bf16 v[96:111], v[180:183], v[116:119], v[96:111]
	s_waitcnt lgkmcnt(1)
	v_mfma_f32_32x32x16_bf16 v[96:111], v[184:187], v[120:123], v[96:111]
	s_waitcnt lgkmcnt(0)
	v_mfma_f32_32x32x16_bf16 v[96:111], v[188:191], v[124:127], v[96:111]
	s_cmp_gt_i32 s33, 2
	s_cbranch_scc1 .LBB0_228
	s_waitcnt lgkmcnt(0)
	v_add_u32_e32 v205, s68, v204
	v_add_u32_e32 v176, 0x17d00, v205
	v_add_u32_e32 v178, 0x17d80, v205
	ds_read2_b32 v[176:177], v176 offset1:1
	ds_read2_b32 v[178:179], v178 offset1:1
	v_add_u32_e32 v180, 0x17d08, v205
	v_add_u32_e32 v182, 0x17d88, v205
	v_add_u32_e32 v184, 0x17d20, v205
	v_add_u32_e32 v186, 0x17da0, v205
	v_add_u32_e32 v188, 0x17d28, v205
	v_add_u32_e32 v190, 0x17da8, v205
	v_add_u32_e32 v206, 0x17d40, v205
	v_add_u32_e32 v210, 0x17dc0, v205
	v_add_u32_e32 v212, 0x17d48, v205
	v_add_u32_e32 v221, 0x17dc8, v205
	ds_read2_b32 v[180:181], v180 offset1:1
	ds_read2_b32 v[182:183], v182 offset1:1
	ds_read2_b32 v[184:185], v184 offset1:1
	ds_read2_b32 v[186:187], v186 offset1:1
	ds_read2_b32 v[188:189], v188 offset1:1
	ds_read2_b32 v[190:191], v190 offset1:1
	ds_read2_b32 v[206:207], v206 offset1:1
	ds_read2_b32 v[210:211], v210 offset1:1
	ds_read2_b32 v[212:213], v212 offset1:1
	ds_read2_b32 v[224:225], v221 offset1:1
	v_add_u32_e32 v221, 0x17d60, v205
	v_add_u32_e32 v223, 0x17de0, v205
	ds_read2_b32 v[226:227], v221 offset1:1
	ds_read2_b32 v[228:229], v223 offset1:1
	v_add_u32_e32 v221, 0x17d68, v205
	v_add_u32_e32 v205, 0x17de8, v205
	ds_read2_b32 v[230:231], v221 offset1:1
	s_waitcnt lgkmcnt(14)
	v_pk_add_f32 v[96:97], v[96:97], v[176:177]
	ds_read2_b32 v[176:177], v205 offset1:1
	s_waitcnt lgkmcnt(3)
	v_pk_add_f32 v[108:109], v[108:109], v[226:227]
	v_pk_add_f32 v[106:107], v[106:107], v[212:213]
	s_waitcnt lgkmcnt(1)
	v_pk_add_f32 v[110:111], v[110:111], v[230:231]
	v_pk_add_f32 v[104:105], v[104:105], v[206:207]
	v_pk_add_f32 v[102:103], v[102:103], v[188:189]
	v_pk_add_f32 v[100:101], v[100:101], v[184:185]
	v_pk_add_f32 v[98:99], v[98:99], v[180:181]
	s_waitcnt lgkmcnt(0)
	v_pk_add_f32 v[94:95], v[94:95], v[176:177]
	v_pk_add_f32 v[92:93], v[92:93], v[228:229]
	v_pk_add_f32 v[90:91], v[90:91], v[224:225]
	v_pk_add_f32 v[88:89], v[88:89], v[210:211]
	v_pk_add_f32 v[86:87], v[86:87], v[190:191]
	v_pk_add_f32 v[84:85], v[84:85], v[186:187]
	v_pk_add_f32 v[82:83], v[82:83], v[182:183]
	v_pk_add_f32 v[80:81], v[80:81], v[178:179]
	s_nop 0
.LBB0_228:
	s_add_i32 s86, s65, -1
	s_bitcmp0_b32 s86, 0
	s_mov_b32 s69, s4
	s_cselect_b32 s28, 0x4400, 0
	s_cselect_b32 s5, 0, 0x4400
	s_mul_i32 s29, s69, 0x5000
	s_addk_i32 s29, 0x5000
	s_cmp_lg_u32 s69, 2
	s_cselect_b32 s29, s29, 0
	s_and_b64 vcc, exec, s[16:17]
	s_cbranch_vccnz .Latt_a
	s_cmp_ge_u32 s65, s66
	s_cbranch_scc1 .Latt_b_sm
	v_add_u32_e32 v176, s28, v157
	s_waitcnt vmcnt(3)
	ds_write_b128 v176, v[128:131]
	v_add_u32_e32 v176, s29, v159
	s_waitcnt vmcnt(2)
	ds_write_b128 v176, v[132:135] offset:34816
	v_add_u32_e32 v176, s28, v161
	s_waitcnt vmcnt(1)
	ds_write_b128 v176, v[136:139]
	v_add_u32_e32 v176, s29, v163
	s_cmp_ge_u32 s86, s8
	s_waitcnt vmcnt(0)
	ds_write_b128 v176, v[140:143] offset:34816
	s_cbranch_scc1 .Latt_b_sm
	v_add_co_u32_e32 v176, vcc, 0xf5ff0000, v174
	s_nop 1
	v_addc_co_u32_e32 v177, vcc, -1, v175, vcc
	v_add_co_u32_e32 v178, vcc, 0xffff0000, v174
	s_nop 1
	v_addc_co_u32_e32 v179, vcc, -1, v175, vcc
	global_load_dwordx4 v[128:131], v[176:177], off
	global_load_dwordx4 v[132:135], v[178:179], off
	v_add_co_u32_e32 v176, vcc, 0xf6000000, v174
	s_nop 1
	v_addc_co_u32_e32 v177, vcc, -1, v175, vcc
	global_load_dwordx4 v[136:139], v[176:177], off
	global_load_dwordx4 v[140:143], v[174:175], off
.Latt_b_sm:
	s_cmp_gt_i32 s86, s9
	s_cbranch_scc1 .Latt_b_bar
	v_max_f32_e32 v176, v80, v80
	v_max_f32_e32 v177, v96, v96
	v_max_f32_e32 v176, v177, v176
	v_max3_f32 v177, v81, v98, v82
	v_max3_f32 v176, v176, v97, v99
	v_max3_f32 v177, v177, v100, v84
	v_max3_f32 v176, v176, v83, v101
	v_max3_f32 v177, v177, v102, v86
	v_max3_f32 v176, v176, v85, v103
	v_max3_f32 v177, v177, v104, v88
	v_max3_f32 v176, v176, v87, v105
	v_max3_f32 v177, v177, v106, v90
	v_max3_f32 v176, v176, v89, v107
	v_max3_f32 v177, v177, v108, v92
	v_max3_f32 v176, v176, v91, v109
	v_max3_f32 v177, v177, v110, v94
	v_max3_f32 v176, v176, v93, v111
	v_max3_f32 v176, v176, v95, v177
	v_mov_b32_e32 v177, v176
	s_nop 1
	v_permlane32_swap_b32_e32 v176, v177
	v_max_f32_e32 v177, v177, v177
	v_max_f32_e32 v176, v176, v176
	v_max_f32_e32 v176, v176, v177
	s_mov_b32 s4, 0x41000000
	v_cmp_lt_f32_e32 vcc, s4, v176
	s_cbranch_vccz .Latt_b_exp
	v_max_f32_e32 v64, v176, v176
	v_max_f32_e32 v66, 0, v64
	v_exp_f32_e64 v176, -v66
	v_add_f32_e32 v173, v173, v66
	v_xor_b32_e32 v64, 0x80000000, v173
	v_pk_add_f32 v[96:97], v[96:97], v[66:67] op_sel_hi:[1,0] neg_lo:[0,1] neg_hi:[0,1]
	v_pk_add_f32 v[80:81], v[80:81], v[66:67] op_sel_hi:[1,0] neg_lo:[0,1] neg_hi:[0,1]
	v_pk_add_f32 v[98:99], v[98:99], v[66:67] op_sel_hi:[1,0] neg_lo:[0,1] neg_hi:[0,1]
	v_pk_add_f32 v[82:83], v[82:83], v[66:67] op_sel_hi:[1,0] neg_lo:[0,1] neg_hi:[0,1]
	v_pk_add_f32 v[100:101], v[100:101], v[66:67] op_sel_hi:[1,0] neg_lo:[0,1] neg_hi:[0,1]
	v_pk_add_f32 v[84:85], v[84:85], v[66:67] op_sel_hi:[1,0] neg_lo:[0,1] neg_hi:[0,1]
	v_pk_add_f32 v[102:103], v[102:103], v[66:67] op_sel_hi:[1,0] neg_lo:[0,1] neg_hi:[0,1]
	v_pk_add_f32 v[86:87], v[86:87], v[66:67] op_sel_hi:[1,0] neg_lo:[0,1] neg_hi:[0,1]
	v_pk_add_f32 v[104:105], v[104:105], v[66:67] op_sel_hi:[1,0] neg_lo:[0,1] neg_hi:[0,1]
	v_pk_add_f32 v[88:89], v[88:89], v[66:67] op_sel_hi:[1,0] neg_lo:[0,1] neg_hi:[0,1]
	v_pk_add_f32 v[106:107], v[106:107], v[66:67] op_sel_hi:[1,0] neg_lo:[0,1] neg_hi:[0,1]
	v_pk_add_f32 v[90:91], v[90:91], v[66:67] op_sel_hi:[1,0] neg_lo:[0,1] neg_hi:[0,1]
	v_pk_add_f32 v[108:109], v[108:109], v[66:67] op_sel_hi:[1,0] neg_lo:[0,1] neg_hi:[0,1]
	v_pk_add_f32 v[92:93], v[92:93], v[66:67] op_sel_hi:[1,0] neg_lo:[0,1] neg_hi:[0,1]
	v_pk_add_f32 v[110:111], v[110:111], v[66:67] op_sel_hi:[1,0] neg_lo:[0,1] neg_hi:[0,1]
	v_pk_add_f32 v[94:95], v[94:95], v[66:67] op_sel_hi:[1,0] neg_lo:[0,1] neg_hi:[0,1]
	v_mov_b32_e32 v65, v64
	v_mov_b32_e32 v66, v64
	v_mov_b32_e32 v67, v64
	v_mov_b32_e32 v68, v64
	v_mov_b32_e32 v69, v64
	v_mov_b32_e32 v70, v64
	v_mov_b32_e32 v71, v64
	v_mov_b32_e32 v72, v64
	v_mov_b32_e32 v73, v64
	v_mov_b32_e32 v74, v64
	v_mov_b32_e32 v75, v64
	v_mov_b32_e32 v76, v64
	v_mov_b32_e32 v77, v64
	v_mov_b32_e32 v78, v64
	v_mov_b32_e32 v79, v64
	v_pk_mul_f32 v[46:47], v[46:47], v[176:177] op_sel_hi:[1,0]
	v_pk_mul_f32 v[44:45], v[44:45], v[176:177] op_sel_hi:[1,0]
	v_pk_mul_f32 v[42:43], v[42:43], v[176:177] op_sel_hi:[1,0]
	v_pk_mul_f32 v[40:41], v[40:41], v[176:177] op_sel_hi:[1,0]
	v_pk_mul_f32 v[38:39], v[38:39], v[176:177] op_sel_hi:[1,0]
	v_pk_mul_f32 v[36:37], v[36:37], v[176:177] op_sel_hi:[1,0]
	v_pk_mul_f32 v[34:35], v[34:35], v[176:177] op_sel_hi:[1,0]
	v_pk_mul_f32 v[32:33], v[32:33], v[176:177] op_sel_hi:[1,0]
	v_pk_mul_f32 v[30:31], v[30:31], v[176:177] op_sel_hi:[1,0]
	v_pk_mul_f32 v[28:29], v[28:29], v[176:177] op_sel_hi:[1,0]
	v_pk_mul_f32 v[26:27], v[26:27], v[176:177] op_sel_hi:[1,0]
	v_pk_mul_f32 v[24:25], v[24:25], v[176:177] op_sel_hi:[1,0]
	v_pk_mul_f32 v[22:23], v[22:23], v[176:177] op_sel_hi:[1,0]
	v_pk_mul_f32 v[20:21], v[20:21], v[176:177] op_sel_hi:[1,0]
	v_pk_mul_f32 v[18:19], v[18:19], v[176:177] op_sel_hi:[1,0]
	v_pk_mul_f32 v[16:17], v[16:17], v[176:177] op_sel_hi:[1,0]
	v_pk_mul_f32 v[14:15], v[14:15], v[176:177] op_sel_hi:[1,0]
	v_pk_mul_f32 v[12:13], v[12:13], v[176:177] op_sel_hi:[1,0]
	v_pk_mul_f32 v[10:11], v[10:11], v[176:177] op_sel_hi:[1,0]
	v_pk_mul_f32 v[8:9], v[8:9], v[176:177] op_sel_hi:[1,0]
	v_pk_mul_f32 v[6:7], v[6:7], v[176:177] op_sel_hi:[1,0]
	v_pk_mul_f32 v[4:5], v[4:5], v[176:177] op_sel_hi:[1,0]
	v_pk_mul_f32 v[2:3], v[2:3], v[176:177] op_sel_hi:[1,0]
	v_pk_mul_f32 v[0:1], v[0:1], v[176:177] op_sel_hi:[1,0]
	v_pk_mul_f32 v[62:63], v[62:63], v[176:177] op_sel_hi:[1,0]
	v_pk_mul_f32 v[60:61], v[60:61], v[176:177] op_sel_hi:[1,0]
	v_pk_mul_f32 v[58:59], v[58:59], v[176:177] op_sel_hi:[1,0]
	v_pk_mul_f32 v[56:57], v[56:57], v[176:177] op_sel_hi:[1,0]
	v_pk_mul_f32 v[54:55], v[54:55], v[176:177] op_sel_hi:[1,0]
	v_pk_mul_f32 v[52:53], v[52:53], v[176:177] op_sel_hi:[1,0]
	v_pk_mul_f32 v[50:51], v[50:51], v[176:177] op_sel_hi:[1,0]
	v_pk_mul_f32 v[48:49], v[48:49], v[176:177] op_sel_hi:[1,0]
	v_mul_f32_e32 v172, v172, v176
.Latt_b_exp:
	v_exp_f32_e32 v96, v96
	v_exp_f32_e32 v97, v97
	v_exp_f32_e32 v176, v80
	v_exp_f32_e32 v177, v81
	v_exp_f32_e32 v98, v98
	v_exp_f32_e32 v99, v99
	v_exp_f32_e32 v178, v82
	v_exp_f32_e32 v179, v83
	v_exp_f32_e32 v100, v100
	v_exp_f32_e32 v101, v101
	v_exp_f32_e32 v180, v84
	v_exp_f32_e32 v181, v85
	v_exp_f32_e32 v102, v102
	v_exp_f32_e32 v103, v103
	v_exp_f32_e32 v182, v86
	v_exp_f32_e32 v183, v87
	v_exp_f32_e32 v104, v104
	v_exp_f32_e32 v105, v105
	v_exp_f32_e32 v184, v88
	v_exp_f32_e32 v185, v89
	v_exp_f32_e32 v106, v106
	v_exp_f32_e32 v107, v107
	v_exp_f32_e32 v186, v90
	v_exp_f32_e32 v187, v91
	v_exp_f32_e32 v108, v108
	v_exp_f32_e32 v109, v109
	v_exp_f32_e32 v188, v92
	v_exp_f32_e32 v189, v93
	v_exp_f32_e32 v110, v110
	v_exp_f32_e32 v111, v111
	v_exp_f32_e32 v190, v94
	v_exp_f32_e32 v191, v95
	v_cvt_pk_bf16_f32 v80, v96, v97
	v_cvt_pk_bf16_f32 v81, v98, v99
	v_cvt_pk_bf16_f32 v82, v100, v101
	v_cvt_pk_bf16_f32 v83, v102, v103
	v_cvt_pk_bf16_f32 v84, v104, v105
	v_cvt_pk_bf16_f32 v85, v106, v107
	v_cvt_pk_bf16_f32 v86, v108, v109
	v_cvt_pk_bf16_f32 v87, v110, v111
	v_cvt_pk_bf16_f32 v88, v176, v177
	v_cvt_pk_bf16_f32 v89, v178, v179
	v_cvt_pk_bf16_f32 v90, v180, v181
	v_cvt_pk_bf16_f32 v91, v182, v183
	v_cvt_pk_bf16_f32 v92, v184, v185
	v_cvt_pk_bf16_f32 v93, v186, v187
	v_cvt_pk_bf16_f32 v94, v188, v189
	v_cvt_pk_bf16_f32 v95, v190, v191
	v_pk_add_f32 v[96:97], v[96:97], 0 op_sel_hi:[1,0]
	s_nop 0
	v_pk_add_f32 v[96:97], v[176:177], v[96:97]
	s_nop 0
	v_pk_add_f32 v[96:97], v[98:99], v[96:97]
	s_nop 0
	v_pk_add_f32 v[96:97], v[178:179], v[96:97]
	s_nop 0
	v_pk_add_f32 v[96:97], v[100:101], v[96:97]
	s_nop 0
	v_pk_add_f32 v[96:97], v[180:181], v[96:97]
	s_nop 0
	v_pk_add_f32 v[96:97], v[102:103], v[96:97]
	s_nop 0
	v_pk_add_f32 v[96:97], v[182:183], v[96:97]
	s_nop 0
	v_pk_add_f32 v[96:97], v[104:105], v[96:97]
	s_nop 0
	v_pk_add_f32 v[96:97], v[184:185], v[96:97]
	s_nop 0
	v_pk_add_f32 v[96:97], v[106:107], v[96:97]
	s_nop 0
	v_pk_add_f32 v[96:97], v[186:187], v[96:97]
	s_nop 0
	v_pk_add_f32 v[96:97], v[108:109], v[96:97]
	s_nop 0
	v_pk_add_f32 v[96:97], v[188:189], v[96:97]
	s_nop 0
	v_pk_add_f32 v[96:97], v[110:111], v[96:97]
	s_nop 0
	v_pk_add_f32 v[96:97], v[190:191], v[96:97]
	s_nop 0
	v_add_f32_e32 v96, v96, v97
	v_add_f32_e32 v172, v172, v96
.Latt_b_bar:
	s_waitcnt lgkmcnt(0)
	s_barrier
	s_cmp_gt_i32 s86, s9
	s_cbranch_scc1 .LBB0_241
	s_cmp_ge_i32 s86, s9
	s_cbranch_scc1 .Latt_b_pvonly
	s_mul_i32 s4, s69, 0x5000
	v_add_u32_e32 v205, s4, v165
	v_add_u32_e32 v206, s28, v192
	ds_read_b64_tr_b16 v[96:97], v205 offset:34816
	ds_read_b64_tr_b16 v[98:99], v205 offset:37376
	ds_read_b64_tr_b16 v[100:101], v205 offset:39936
	ds_read_b64_tr_b16 v[102:103], v205 offset:42496
	ds_read_b64_tr_b16 v[104:105], v205 offset:45056
	ds_read_b64_tr_b16 v[106:107], v205 offset:47616
	ds_read_b64_tr_b16 v[108:109], v205 offset:50176
	ds_read_b64_tr_b16 v[110:111], v205 offset:52736
	ds_read_b64_tr_b16 v[176:177], v205 offset:34880
	ds_read_b64_tr_b16 v[178:179], v205 offset:37440
	ds_read_b64_tr_b16 v[180:181], v205 offset:40000
	ds_read_b64_tr_b16 v[182:183], v205 offset:42560
	ds_read_b64_tr_b16 v[184:185], v205 offset:45120
	ds_read_b64_tr_b16 v[186:187], v205 offset:47680
	s_setprio 1
	s_waitcnt lgkmcnt(12)
	v_mfma_f32_32x32x16_bf16 v[32:47], v[96:99], v[80:83], v[32:47]
	s_setprio 0
	ds_read_b64_tr_b16 v[96:97], v205 offset:50240
	ds_read_b64_tr_b16 v[98:99], v205 offset:52800
	s_setprio 1
	s_waitcnt lgkmcnt(12)
	v_mfma_f32_32x32x16_bf16 v[32:47], v[100:103], v[84:87], v[32:47]
	s_setprio 0
	ds_read_b64_tr_b16 v[100:101], v205 offset:34944
	ds_read_b64_tr_b16 v[102:103], v205 offset:37504
	s_setprio 1
	s_waitcnt lgkmcnt(12)
	v_mfma_f32_32x32x16_bf16 v[32:47], v[104:107], v[88:91], v[32:47]
	s_setprio 0
	ds_read_b64_tr_b16 v[104:105], v205 offset:40064
	ds_read_b64_tr_b16 v[106:107], v205 offset:42624
	s_setprio 1
	s_waitcnt lgkmcnt(12)
	v_mfma_f32_32x32x16_bf16 v[32:47], v[108:111], v[92:95], v[32:47]
	s_setprio 0
	ds_read_b64_tr_b16 v[108:109], v205 offset:45184
	ds_read_b64_tr_b16 v[110:111], v205 offset:47744
	s_setprio 1
	s_waitcnt lgkmcnt(12)
	v_mfma_f32_32x32x16_bf16 v[16:31], v[176:179], v[80:83], v[16:31]
	s_setprio 0
	ds_read_b64_tr_b16 v[176:177], v205 offset:50304
	ds_read_b64_tr_b16 v[178:179], v205 offset:52864
	s_setprio 1
	s_waitcnt lgkmcnt(12)
	v_mfma_f32_32x32x16_bf16 v[16:31], v[180:183], v[84:87], v[16:31]
	s_setprio 0
	ds_read_b64_tr_b16 v[180:181], v205 offset:35008
	ds_read_b64_tr_b16 v[182:183], v205 offset:37568
	s_setprio 1
	s_waitcnt lgkmcnt(12)
	v_mfma_f32_32x32x16_bf16 v[16:31], v[184:187], v[88:91], v[16:31]
	s_setprio 0
	ds_read_b64_tr_b16 v[184:185], v205 offset:40128
	ds_read_b64_tr_b16 v[186:187], v205 offset:42688
	s_setprio 1
	s_waitcnt lgkmcnt(12)
	v_mfma_f32_32x32x16_bf16 v[16:31], v[96:99], v[92:95], v[16:31]
	s_setprio 0
	ds_read_b64_tr_b16 v[96:97], v205 offset:45248
	ds_read_b64_tr_b16 v[98:99], v205 offset:47808
	s_setprio 1
	s_waitcnt lgkmcnt(12)
	v_mfma_f32_32x32x16_bf16 v[0:15], v[100:103], v[80:83], v[0:15]
	s_setprio 0
	ds_read_b64_tr_b16 v[100:101], v205 offset:50368
	ds_read_b64_tr_b16 v[102:103], v205 offset:52928
	s_setprio 1
	s_waitcnt lgkmcnt(12)
	v_mfma_f32_32x32x16_bf16 v[0:15], v[104:107], v[84:87], v[0:15]
	s_setprio 0
	ds_read_b128 v[210:213], v206 offset:8704
	ds_read_b128 v[104:107], v206 offset:8736
	s_setprio 1
	s_waitcnt lgkmcnt(12)
	v_mfma_f32_32x32x16_bf16 v[0:15], v[108:111], v[88:91], v[0:15]
	s_setprio 0
	ds_read_b128 v[108:111], v206 offset:8768
	ds_read_b128 v[188:191], v206
	s_setprio 1
	s_waitcnt lgkmcnt(12)
	v_mfma_f32_32x32x16_bf16 v[0:15], v[176:179], v[92:95], v[0:15]
	s_setprio 0
	ds_read_b128 v[176:179], v206 offset:8800
	ds_read_b128 v[224:227], v206 offset:32
	s_setprio 1
	s_waitcnt lgkmcnt(12)
	v_mfma_f32_32x32x16_bf16 v[48:63], v[180:183], v[80:83], v[48:63]
	s_setprio 0
	ds_read_b128 v[228:231], v206 offset:64
	ds_read_b128 v[248:251], v206 offset:96
	s_setprio 1
	s_waitcnt lgkmcnt(12)
	v_mfma_f32_32x32x16_bf16 v[48:63], v[184:187], v[84:87], v[48:63]
	s_setprio 0
	s_setprio 1
	s_waitcnt lgkmcnt(10)
	v_mfma_f32_32x32x16_bf16 v[48:63], v[96:99], v[88:91], v[48:63]
	s_setprio 0
	s_setprio 1
	s_waitcnt lgkmcnt(8)
	v_mfma_f32_32x32x16_bf16 v[48:63], v[100:103], v[92:95], v[48:63]
	s_setprio 0
	s_waitcnt lgkmcnt(7)
	v_mfma_f32_32x32x16_bf16 v[80:95], v[210:213], v[112:115], v[64:79]
	s_waitcnt lgkmcnt(6)
	v_mfma_f32_32x32x16_bf16 v[80:95], v[104:107], v[116:119], v[80:95]
	s_waitcnt lgkmcnt(5)
	v_mfma_f32_32x32x16_bf16 v[80:95], v[108:111], v[120:123], v[80:95]
	s_waitcnt lgkmcnt(3)
	v_mfma_f32_32x32x16_bf16 v[80:95], v[176:179], v[124:127], v[80:95]
	s_waitcnt lgkmcnt(4)
	v_mfma_f32_32x32x16_bf16 v[96:111], v[188:191], v[112:115], v[64:79]
	s_waitcnt lgkmcnt(2)
	v_mfma_f32_32x32x16_bf16 v[96:111], v[224:227], v[116:119], v[96:111]
	s_waitcnt lgkmcnt(1)
	v_mfma_f32_32x32x16_bf16 v[96:111], v[228:231], v[120:123], v[96:111]
	s_waitcnt lgkmcnt(0)
	v_mfma_f32_32x32x16_bf16 v[96:111], v[248:251], v[124:127], v[96:111]
	s_cmp_gt_i32 s33, 3
	s_cbranch_scc1 .LBB0_241
	s_waitcnt lgkmcnt(0)
	s_add_i32 s4, s68, 0x100
	v_add_u32_e32 v205, s4, v204
	v_add_u32_e32 v176, 0x17d00, v205
	v_add_u32_e32 v178, 0x17d80, v205
	ds_read2_b32 v[176:177], v176 offset1:1
	ds_read2_b32 v[178:179], v178 offset1:1
	v_add_u32_e32 v180, 0x17d08, v205
	v_add_u32_e32 v182, 0x17d88, v205
	v_add_u32_e32 v184, 0x17d20, v205
	v_add_u32_e32 v186, 0x17da0, v205
	v_add_u32_e32 v188, 0x17d28, v205
	v_add_u32_e32 v190, 0x17da8, v205
	v_add_u32_e32 v206, 0x17d40, v205
	v_add_u32_e32 v210, 0x17dc0, v205
	v_add_u32_e32 v212, 0x17d48, v205
	v_add_u32_e32 v221, 0x17dc8, v205
	ds_read2_b32 v[180:181], v180 offset1:1
	ds_read2_b32 v[182:183], v182 offset1:1
	ds_read2_b32 v[184:185], v184 offset1:1
	ds_read2_b32 v[186:187], v186 offset1:1
	ds_read2_b32 v[188:189], v188 offset1:1
	ds_read2_b32 v[190:191], v190 offset1:1
	ds_read2_b32 v[206:207], v206 offset1:1
	ds_read2_b32 v[210:211], v210 offset1:1
	ds_read2_b32 v[212:213], v212 offset1:1
	ds_read2_b32 v[224:225], v221 offset1:1
	v_add_u32_e32 v221, 0x17d60, v205
	v_add_u32_e32 v223, 0x17de0, v205
	ds_read2_b32 v[226:227], v221 offset1:1
	ds_read2_b32 v[228:229], v223 offset1:1
	v_add_u32_e32 v221, 0x17d68, v205
	v_add_u32_e32 v205, 0x17de8, v205
	ds_read2_b32 v[230:231], v221 offset1:1
	s_waitcnt lgkmcnt(14)
	v_pk_add_f32 v[96:97], v[96:97], v[176:177]
	ds_read2_b32 v[176:177], v205 offset1:1
	s_waitcnt lgkmcnt(3)
	v_pk_add_f32 v[108:109], v[108:109], v[226:227]
	v_pk_add_f32 v[106:107], v[106:107], v[212:213]
	s_waitcnt lgkmcnt(1)
	v_pk_add_f32 v[110:111], v[110:111], v[230:231]
	v_pk_add_f32 v[104:105], v[104:105], v[206:207]
	v_pk_add_f32 v[102:103], v[102:103], v[188:189]
	v_pk_add_f32 v[100:101], v[100:101], v[184:185]
	v_pk_add_f32 v[98:99], v[98:99], v[180:181]
	s_waitcnt lgkmcnt(0)
	v_pk_add_f32 v[94:95], v[94:95], v[176:177]
	v_pk_add_f32 v[92:93], v[92:93], v[228:229]
	v_pk_add_f32 v[90:91], v[90:91], v[224:225]
	v_pk_add_f32 v[88:89], v[88:89], v[210:211]
	v_pk_add_f32 v[86:87], v[86:87], v[190:191]
	v_pk_add_f32 v[84:85], v[84:85], v[186:187]
	v_pk_add_f32 v[82:83], v[82:83], v[182:183]
	v_pk_add_f32 v[80:81], v[80:81], v[178:179]
	s_nop 0
	s_branch .LBB0_241
.Latt_b_pvonly:
	s_mul_i32 s4, s69, 0x5000
	v_add_u32_e32 v205, s4, v165
	ds_read_b64_tr_b16 v[224:225], v205 offset:34816
	ds_read_b64_tr_b16 v[226:227], v205 offset:37376
	ds_read_b64_tr_b16 v[228:229], v205 offset:39936
	ds_read_b64_tr_b16 v[230:231], v205 offset:42496
	ds_read_b64_tr_b16 v[248:249], v205 offset:45056
	ds_read_b64_tr_b16 v[250:251], v205 offset:47616
	ds_read_b64_tr_b16 v[210:211], v205 offset:50176
	ds_read_b64_tr_b16 v[212:213], v205 offset:52736
	s_setprio 1
	s_waitcnt lgkmcnt(6)
	v_mfma_f32_32x32x16_bf16 v[32:47], v[224:227], v[80:83], v[32:47]
	s_setprio 0
	ds_read_b64_tr_b16 v[224:225], v205 offset:34880
	ds_read_b64_tr_b16 v[226:227], v205 offset:37440
	s_setprio 1
	s_waitcnt lgkmcnt(6)
	v_mfma_f32_32x32x16_bf16 v[32:47], v[228:231], v[84:87], v[32:47]
	s_setprio 0
	ds_read_b64_tr_b16 v[228:229], v205 offset:40000
	ds_read_b64_tr_b16 v[230:231], v205 offset:42560
	s_setprio 1
	s_waitcnt lgkmcnt(6)
	v_mfma_f32_32x32x16_bf16 v[32:47], v[248:251], v[88:91], v[32:47]
	s_setprio 0
	ds_read_b64_tr_b16 v[248:249], v205 offset:45120
	ds_read_b64_tr_b16 v[250:251], v205 offset:47680
	s_setprio 1
	s_waitcnt lgkmcnt(6)
	v_mfma_f32_32x32x16_bf16 v[32:47], v[210:213], v[92:95], v[32:47]
	s_setprio 0
	ds_read_b64_tr_b16 v[210:211], v205 offset:50240
	ds_read_b64_tr_b16 v[212:213], v205 offset:52800
	s_setprio 1
	s_waitcnt lgkmcnt(6)
	v_mfma_f32_32x32x16_bf16 v[16:31], v[224:227], v[80:83], v[16:31]
	s_setprio 0
	ds_read_b64_tr_b16 v[224:225], v205 offset:34944
	ds_read_b64_tr_b16 v[226:227], v205 offset:37504
	s_setprio 1
	s_waitcnt lgkmcnt(6)
	v_mfma_f32_32x32x16_bf16 v[16:31], v[228:231], v[84:87], v[16:31]
	s_setprio 0
	ds_read_b64_tr_b16 v[228:229], v205 offset:40064
	ds_read_b64_tr_b16 v[230:231], v205 offset:42624
	s_setprio 1
	s_waitcnt lgkmcnt(6)
	v_mfma_f32_32x32x16_bf16 v[16:31], v[248:251], v[88:91], v[16:31]
	s_setprio 0
	ds_read_b64_tr_b16 v[248:249], v205 offset:45184
	ds_read_b64_tr_b16 v[250:251], v205 offset:47744
	s_setprio 1
	s_waitcnt lgkmcnt(6)
	v_mfma_f32_32x32x16_bf16 v[16:31], v[210:213], v[92:95], v[16:31]
	s_setprio 0
	ds_read_b64_tr_b16 v[210:211], v205 offset:50304
	ds_read_b64_tr_b16 v[212:213], v205 offset:52864
	s_setprio 1
	s_waitcnt lgkmcnt(6)
	v_mfma_f32_32x32x16_bf16 v[0:15], v[224:227], v[80:83], v[0:15]
	s_setprio 0
	ds_read_b64_tr_b16 v[224:225], v205 offset:35008
	ds_read_b64_tr_b16 v[226:227], v205 offset:37568
	s_setprio 1
	s_waitcnt lgkmcnt(6)
	v_mfma_f32_32x32x16_bf16 v[0:15], v[228:231], v[84:87], v[0:15]
	s_setprio 0
	ds_read_b64_tr_b16 v[228:229], v205 offset:40128
	ds_read_b64_tr_b16 v[230:231], v205 offset:42688
	s_setprio 1
	s_waitcnt lgkmcnt(6)
	v_mfma_f32_32x32x16_bf16 v[0:15], v[248:251], v[88:91], v[0:15]
	s_setprio 0
	ds_read_b64_tr_b16 v[248:249], v205 offset:45248
	ds_read_b64_tr_b16 v[250:251], v205 offset:47808
	s_setprio 1
	s_waitcnt lgkmcnt(6)
	v_mfma_f32_32x32x16_bf16 v[0:15], v[210:213], v[92:95], v[0:15]
	s_setprio 0
	ds_read_b64_tr_b16 v[210:211], v205 offset:50368
	ds_read_b64_tr_b16 v[212:213], v205 offset:52928
	s_setprio 1
	s_waitcnt lgkmcnt(6)
	v_mfma_f32_32x32x16_bf16 v[48:63], v[224:227], v[80:83], v[48:63]
	s_setprio 0
	s_setprio 1
	s_waitcnt lgkmcnt(4)
	v_mfma_f32_32x32x16_bf16 v[48:63], v[228:231], v[84:87], v[48:63]
	s_setprio 0
	s_setprio 1
	s_waitcnt lgkmcnt(2)
	v_mfma_f32_32x32x16_bf16 v[48:63], v[248:251], v[88:91], v[48:63]
	s_setprio 0
	s_setprio 1
	s_waitcnt lgkmcnt(0)
	v_mfma_f32_32x32x16_bf16 v[48:63], v[210:213], v[92:95], v[48:63]
	s_setprio 0
	s_branch .LBB0_241
.Latt_a:
	s_mul_i32 s4, s87, 0x5000
	v_add_u32_e32 v205, s4, v165
	v_add_u32_e32 v206, s5, v192
	ds_read_b64_tr_b16 v[96:97], v205 offset:34816
	ds_read_b64_tr_b16 v[98:99], v205 offset:37376
	ds_read_b64_tr_b16 v[100:101], v205 offset:39936
	ds_read_b64_tr_b16 v[102:103], v205 offset:42496
	ds_read_b64_tr_b16 v[104:105], v205 offset:45056
	ds_read_b64_tr_b16 v[106:107], v205 offset:47616
	ds_read_b64_tr_b16 v[108:109], v205 offset:50176
	ds_read_b64_tr_b16 v[110:111], v205 offset:52736
	ds_read_b64_tr_b16 v[176:177], v205 offset:34880
	ds_read_b64_tr_b16 v[178:179], v205 offset:37440
	ds_read_b64_tr_b16 v[180:181], v205 offset:40000
	ds_read_b64_tr_b16 v[182:183], v205 offset:42560
	ds_read_b64_tr_b16 v[184:185], v205 offset:45120
	ds_read_b64_tr_b16 v[186:187], v205 offset:47680
	s_setprio 1
	s_waitcnt lgkmcnt(12)
	v_mfma_f32_32x32x16_bf16 v[32:47], v[96:99], v[80:83], v[32:47]
	s_setprio 0
	ds_read_b64_tr_b16 v[96:97], v205 offset:50240
	ds_read_b64_tr_b16 v[98:99], v205 offset:52800
	s_setprio 1
	s_waitcnt lgkmcnt(12)
	v_mfma_f32_32x32x16_bf16 v[32:47], v[100:103], v[84:87], v[32:47]
	s_setprio 0
	ds_read_b64_tr_b16 v[100:101], v205 offset:34944
	ds_read_b64_tr_b16 v[102:103], v205 offset:37504
	s_setprio 1
	s_waitcnt lgkmcnt(12)
	v_mfma_f32_32x32x16_bf16 v[32:47], v[104:107], v[88:91], v[32:47]
	s_setprio 0
	ds_read_b64_tr_b16 v[104:105], v205 offset:40064
	ds_read_b64_tr_b16 v[106:107], v205 offset:42624
	s_setprio 1
	s_waitcnt lgkmcnt(12)
	v_mfma_f32_32x32x16_bf16 v[32:47], v[108:111], v[92:95], v[32:47]
	s_setprio 0
	ds_read_b64_tr_b16 v[108:109], v205 offset:45184
	ds_read_b64_tr_b16 v[110:111], v205 offset:47744
	s_setprio 1
	s_waitcnt lgkmcnt(12)
	v_mfma_f32_32x32x16_bf16 v[16:31], v[176:179], v[80:83], v[16:31]
	s_setprio 0
	ds_read_b64_tr_b16 v[176:177], v205 offset:50304
	ds_read_b64_tr_b16 v[178:179], v205 offset:52864
	s_setprio 1
	s_waitcnt lgkmcnt(12)
	v_mfma_f32_32x32x16_bf16 v[16:31], v[180:183], v[84:87], v[16:31]
	s_setprio 0
	ds_read_b64_tr_b16 v[180:181], v205 offset:35008
	ds_read_b64_tr_b16 v[182:183], v205 offset:37568
	s_setprio 1
	s_waitcnt lgkmcnt(12)
	v_mfma_f32_32x32x16_bf16 v[16:31], v[184:187], v[88:91], v[16:31]
	s_setprio 0
	ds_read_b64_tr_b16 v[184:185], v205 offset:40128
	ds_read_b64_tr_b16 v[186:187], v205 offset:42688
	s_setprio 1
	s_waitcnt lgkmcnt(12)
	v_mfma_f32_32x32x16_bf16 v[16:31], v[96:99], v[92:95], v[16:31]
	s_setprio 0
	ds_read_b64_tr_b16 v[96:97], v205 offset:45248
	ds_read_b64_tr_b16 v[98:99], v205 offset:47808
	s_setprio 1
	s_waitcnt lgkmcnt(12)
	v_mfma_f32_32x32x16_bf16 v[0:15], v[100:103], v[80:83], v[0:15]
	s_setprio 0
	ds_read_b64_tr_b16 v[100:101], v205 offset:50368
	ds_read_b64_tr_b16 v[102:103], v205 offset:52928
	s_setprio 1
	s_waitcnt lgkmcnt(12)
	v_mfma_f32_32x32x16_bf16 v[0:15], v[104:107], v[84:87], v[0:15]
	s_setprio 0
	ds_read_b128 v[210:213], v206 offset:8704
	ds_read_b128 v[104:107], v206 offset:8736
	s_setprio 1
	s_waitcnt lgkmcnt(12)
	v_mfma_f32_32x32x16_bf16 v[0:15], v[108:111], v[88:91], v[0:15]
	s_setprio 0
	ds_read_b128 v[108:111], v206 offset:8768
	ds_read_b128 v[188:191], v206
	s_setprio 1
	s_waitcnt lgkmcnt(12)
	v_mfma_f32_32x32x16_bf16 v[0:15], v[176:179], v[92:95], v[0:15]
	s_setprio 0
	ds_read_b128 v[176:179], v206 offset:8800
	ds_read_b128 v[224:227], v206 offset:32
	s_setprio 1
	s_waitcnt lgkmcnt(12)
	v_mfma_f32_32x32x16_bf16 v[48:63], v[180:183], v[80:83], v[48:63]
	s_setprio 0
	ds_read_b128 v[228:231], v206 offset:64
	ds_read_b128 v[248:251], v206 offset:96
	s_setprio 1
	s_waitcnt lgkmcnt(12)
	v_mfma_f32_32x32x16_bf16 v[48:63], v[184:187], v[84:87], v[48:63]
	s_setprio 0
	s_setprio 1
	s_waitcnt lgkmcnt(10)
	v_mfma_f32_32x32x16_bf16 v[48:63], v[96:99], v[88:91], v[48:63]
	s_setprio 0
	s_setprio 1
	s_waitcnt lgkmcnt(8)
	v_mfma_f32_32x32x16_bf16 v[48:63], v[100:103], v[92:95], v[48:63]
	s_setprio 0
	s_waitcnt lgkmcnt(7)
	v_mfma_f32_32x32x16_bf16 v[80:95], v[210:213], v[112:115], v[64:79]
	s_waitcnt lgkmcnt(6)
	v_mfma_f32_32x32x16_bf16 v[80:95], v[104:107], v[116:119], v[80:95]
	s_waitcnt lgkmcnt(5)
	v_mfma_f32_32x32x16_bf16 v[80:95], v[108:111], v[120:123], v[80:95]
	s_waitcnt lgkmcnt(3)
	v_mfma_f32_32x32x16_bf16 v[80:95], v[176:179], v[124:127], v[80:95]
	s_waitcnt lgkmcnt(4)
	v_mfma_f32_32x32x16_bf16 v[96:111], v[188:191], v[112:115], v[64:79]
	s_waitcnt lgkmcnt(2)
	v_mfma_f32_32x32x16_bf16 v[96:111], v[224:227], v[116:119], v[96:111]
	s_waitcnt lgkmcnt(1)
	v_mfma_f32_32x32x16_bf16 v[96:111], v[228:231], v[120:123], v[96:111]
	s_waitcnt lgkmcnt(0)
	v_mfma_f32_32x32x16_bf16 v[96:111], v[248:251], v[124:127], v[96:111]
	s_cmp_gt_i32 s33, 2
	s_cbranch_scc1 .Latt_a_stg
	s_waitcnt lgkmcnt(0)
	v_add_u32_e32 v205, s68, v204
	v_add_u32_e32 v176, 0x17d00, v205
	v_add_u32_e32 v178, 0x17d80, v205
	ds_read2_b32 v[176:177], v176 offset1:1
	ds_read2_b32 v[178:179], v178 offset1:1
	v_add_u32_e32 v180, 0x17d08, v205
	v_add_u32_e32 v182, 0x17d88, v205
	v_add_u32_e32 v184, 0x17d20, v205
	v_add_u32_e32 v186, 0x17da0, v205
	v_add_u32_e32 v188, 0x17d28, v205
	v_add_u32_e32 v190, 0x17da8, v205
	v_add_u32_e32 v206, 0x17d40, v205
	v_add_u32_e32 v210, 0x17dc0, v205
	v_add_u32_e32 v212, 0x17d48, v205
	v_add_u32_e32 v221, 0x17dc8, v205
	ds_read2_b32 v[180:181], v180 offset1:1
	ds_read2_b32 v[182:183], v182 offset1:1
	ds_read2_b32 v[184:185], v184 offset1:1
	ds_read2_b32 v[186:187], v186 offset1:1
	ds_read2_b32 v[188:189], v188 offset1:1
	ds_read2_b32 v[190:191], v190 offset1:1
	ds_read2_b32 v[206:207], v206 offset1:1
	ds_read2_b32 v[210:211], v210 offset1:1
	ds_read2_b32 v[212:213], v212 offset1:1
	ds_read2_b32 v[224:225], v221 offset1:1
	v_add_u32_e32 v221, 0x17d60, v205
	v_add_u32_e32 v223, 0x17de0, v205
	ds_read2_b32 v[226:227], v221 offset1:1
	ds_read2_b32 v[228:229], v223 offset1:1
	v_add_u32_e32 v221, 0x17d68, v205
	v_add_u32_e32 v205, 0x17de8, v205
	ds_read2_b32 v[230:231], v221 offset1:1
	s_waitcnt lgkmcnt(14)
	v_pk_add_f32 v[96:97], v[96:97], v[176:177]
	ds_read2_b32 v[176:177], v205 offset1:1
	s_waitcnt lgkmcnt(3)
	v_pk_add_f32 v[108:109], v[108:109], v[226:227]
	v_pk_add_f32 v[106:107], v[106:107], v[212:213]
	s_waitcnt lgkmcnt(1)
	v_pk_add_f32 v[110:111], v[110:111], v[230:231]
	v_pk_add_f32 v[104:105], v[104:105], v[206:207]
	v_pk_add_f32 v[102:103], v[102:103], v[188:189]
	v_pk_add_f32 v[100:101], v[100:101], v[184:185]
	v_pk_add_f32 v[98:99], v[98:99], v[180:181]
	s_waitcnt lgkmcnt(0)
	v_pk_add_f32 v[94:95], v[94:95], v[176:177]
	v_pk_add_f32 v[92:93], v[92:93], v[228:229]
	v_pk_add_f32 v[90:91], v[90:91], v[224:225]
	v_pk_add_f32 v[88:89], v[88:89], v[210:211]
	v_pk_add_f32 v[86:87], v[86:87], v[190:191]
	v_pk_add_f32 v[84:85], v[84:85], v[186:187]
	v_pk_add_f32 v[82:83], v[82:83], v[182:183]
	v_pk_add_f32 v[80:81], v[80:81], v[178:179]
	s_nop 0
.Latt_a_stg:
	s_cmp_ge_u32 s65, s66
	s_cbranch_scc1 .Latt_a_bar
	v_add_u32_e32 v176, s28, v157
	s_waitcnt vmcnt(3)
	ds_write_b128 v176, v[128:131]
	v_add_u32_e32 v176, s29, v159
	s_waitcnt vmcnt(2)
	ds_write_b128 v176, v[132:135] offset:34816
	v_add_u32_e32 v176, s28, v161
	s_waitcnt vmcnt(1)
	ds_write_b128 v176, v[136:139]
	v_add_u32_e32 v176, s29, v163
	s_cmp_ge_u32 s86, s8
	s_waitcnt vmcnt(0)
	ds_write_b128 v176, v[140:143] offset:34816
	s_cbranch_scc1 .Latt_a_bar
	v_add_co_u32_e32 v176, vcc, 0xf5ff0000, v174
	s_nop 1
	v_addc_co_u32_e32 v177, vcc, -1, v175, vcc
	v_add_co_u32_e32 v178, vcc, 0xffff0000, v174
	s_nop 1
	v_addc_co_u32_e32 v179, vcc, -1, v175, vcc
	global_load_dwordx4 v[128:131], v[176:177], off
	global_load_dwordx4 v[132:135], v[178:179], off
	v_add_co_u32_e32 v176, vcc, 0xf6000000, v174
	s_nop 1
	v_addc_co_u32_e32 v177, vcc, -1, v175, vcc
	global_load_dwordx4 v[136:139], v[176:177], off
	global_load_dwordx4 v[140:143], v[174:175], off
.Latt_a_bar:
	s_waitcnt lgkmcnt(0)
	s_barrier
	s_nop 9
	v_max_f32_e32 v176, v80, v80
	v_max_f32_e32 v177, v96, v96
	v_max_f32_e32 v176, v177, v176
	v_max3_f32 v177, v81, v98, v82
	v_max3_f32 v176, v176, v97, v99
	v_max3_f32 v177, v177, v100, v84
	v_max3_f32 v176, v176, v83, v101
	v_max3_f32 v177, v177, v102, v86
	v_max3_f32 v176, v176, v85, v103
	v_max3_f32 v177, v177, v104, v88
	v_max3_f32 v176, v176, v87, v105
	v_max3_f32 v177, v177, v106, v90
	v_max3_f32 v176, v176, v89, v107
	v_max3_f32 v177, v177, v108, v92
	v_max3_f32 v176, v176, v91, v109
	v_max3_f32 v177, v177, v110, v94
	v_max3_f32 v176, v176, v93, v111
	v_max3_f32 v176, v176, v95, v177
	v_mov_b32_e32 v177, v176
	s_nop 1
	v_permlane32_swap_b32_e32 v176, v177
	v_max_f32_e32 v177, v177, v177
	v_max_f32_e32 v176, v176, v176
	v_max_f32_e32 v176, v176, v177
	s_mov_b32 s4, 0x41000000
	v_cmp_lt_f32_e32 vcc, s4, v176
	s_cbranch_vccz .Latt_a_exp
	v_max_f32_e32 v64, v176, v176
	v_max_f32_e32 v66, 0, v64
	v_exp_f32_e64 v176, -v66
	v_add_f32_e32 v173, v173, v66
	v_xor_b32_e32 v64, 0x80000000, v173
	v_pk_add_f32 v[96:97], v[96:97], v[66:67] op_sel_hi:[1,0] neg_lo:[0,1] neg_hi:[0,1]
	v_pk_add_f32 v[80:81], v[80:81], v[66:67] op_sel_hi:[1,0] neg_lo:[0,1] neg_hi:[0,1]
	v_pk_add_f32 v[98:99], v[98:99], v[66:67] op_sel_hi:[1,0] neg_lo:[0,1] neg_hi:[0,1]
	v_pk_add_f32 v[82:83], v[82:83], v[66:67] op_sel_hi:[1,0] neg_lo:[0,1] neg_hi:[0,1]
	v_pk_add_f32 v[100:101], v[100:101], v[66:67] op_sel_hi:[1,0] neg_lo:[0,1] neg_hi:[0,1]
	v_pk_add_f32 v[84:85], v[84:85], v[66:67] op_sel_hi:[1,0] neg_lo:[0,1] neg_hi:[0,1]
	v_pk_add_f32 v[102:103], v[102:103], v[66:67] op_sel_hi:[1,0] neg_lo:[0,1] neg_hi:[0,1]
	v_pk_add_f32 v[86:87], v[86:87], v[66:67] op_sel_hi:[1,0] neg_lo:[0,1] neg_hi:[0,1]
	v_pk_add_f32 v[104:105], v[104:105], v[66:67] op_sel_hi:[1,0] neg_lo:[0,1] neg_hi:[0,1]
	v_pk_add_f32 v[88:89], v[88:89], v[66:67] op_sel_hi:[1,0] neg_lo:[0,1] neg_hi:[0,1]
	v_pk_add_f32 v[106:107], v[106:107], v[66:67] op_sel_hi:[1,0] neg_lo:[0,1] neg_hi:[0,1]
	v_pk_add_f32 v[90:91], v[90:91], v[66:67] op_sel_hi:[1,0] neg_lo:[0,1] neg_hi:[0,1]
	v_pk_add_f32 v[108:109], v[108:109], v[66:67] op_sel_hi:[1,0] neg_lo:[0,1] neg_hi:[0,1]
	v_pk_add_f32 v[92:93], v[92:93], v[66:67] op_sel_hi:[1,0] neg_lo:[0,1] neg_hi:[0,1]
	v_pk_add_f32 v[110:111], v[110:111], v[66:67] op_sel_hi:[1,0] neg_lo:[0,1] neg_hi:[0,1]
	v_pk_add_f32 v[94:95], v[94:95], v[66:67] op_sel_hi:[1,0] neg_lo:[0,1] neg_hi:[0,1]
	v_mov_b32_e32 v65, v64
	v_mov_b32_e32 v66, v64
	v_mov_b32_e32 v67, v64
	v_mov_b32_e32 v68, v64
	v_mov_b32_e32 v69, v64
	v_mov_b32_e32 v70, v64
	v_mov_b32_e32 v71, v64
	v_mov_b32_e32 v72, v64
	v_mov_b32_e32 v73, v64
	v_mov_b32_e32 v74, v64
	v_mov_b32_e32 v75, v64
	v_mov_b32_e32 v76, v64
	v_mov_b32_e32 v77, v64
	v_mov_b32_e32 v78, v64
	v_mov_b32_e32 v79, v64
	v_pk_mul_f32 v[46:47], v[46:47], v[176:177] op_sel_hi:[1,0]
	v_pk_mul_f32 v[44:45], v[44:45], v[176:177] op_sel_hi:[1,0]
	v_pk_mul_f32 v[42:43], v[42:43], v[176:177] op_sel_hi:[1,0]
	v_pk_mul_f32 v[40:41], v[40:41], v[176:177] op_sel_hi:[1,0]
	v_pk_mul_f32 v[38:39], v[38:39], v[176:177] op_sel_hi:[1,0]
	v_pk_mul_f32 v[36:37], v[36:37], v[176:177] op_sel_hi:[1,0]
	v_pk_mul_f32 v[34:35], v[34:35], v[176:177] op_sel_hi:[1,0]
	v_pk_mul_f32 v[32:33], v[32:33], v[176:177] op_sel_hi:[1,0]
	v_pk_mul_f32 v[30:31], v[30:31], v[176:177] op_sel_hi:[1,0]
	v_pk_mul_f32 v[28:29], v[28:29], v[176:177] op_sel_hi:[1,0]
	v_pk_mul_f32 v[26:27], v[26:27], v[176:177] op_sel_hi:[1,0]
	v_pk_mul_f32 v[24:25], v[24:25], v[176:177] op_sel_hi:[1,0]
	v_pk_mul_f32 v[22:23], v[22:23], v[176:177] op_sel_hi:[1,0]
	v_pk_mul_f32 v[20:21], v[20:21], v[176:177] op_sel_hi:[1,0]
	v_pk_mul_f32 v[18:19], v[18:19], v[176:177] op_sel_hi:[1,0]
	v_pk_mul_f32 v[16:17], v[16:17], v[176:177] op_sel_hi:[1,0]
	v_pk_mul_f32 v[14:15], v[14:15], v[176:177] op_sel_hi:[1,0]
	v_pk_mul_f32 v[12:13], v[12:13], v[176:177] op_sel_hi:[1,0]
	v_pk_mul_f32 v[10:11], v[10:11], v[176:177] op_sel_hi:[1,0]
	v_pk_mul_f32 v[8:9], v[8:9], v[176:177] op_sel_hi:[1,0]
	v_pk_mul_f32 v[6:7], v[6:7], v[176:177] op_sel_hi:[1,0]
	v_pk_mul_f32 v[4:5], v[4:5], v[176:177] op_sel_hi:[1,0]
	v_pk_mul_f32 v[2:3], v[2:3], v[176:177] op_sel_hi:[1,0]
	v_pk_mul_f32 v[0:1], v[0:1], v[176:177] op_sel_hi:[1,0]
	v_pk_mul_f32 v[62:63], v[62:63], v[176:177] op_sel_hi:[1,0]
	v_pk_mul_f32 v[60:61], v[60:61], v[176:177] op_sel_hi:[1,0]
	v_pk_mul_f32 v[58:59], v[58:59], v[176:177] op_sel_hi:[1,0]
	v_pk_mul_f32 v[56:57], v[56:57], v[176:177] op_sel_hi:[1,0]
	v_pk_mul_f32 v[54:55], v[54:55], v[176:177] op_sel_hi:[1,0]
	v_pk_mul_f32 v[52:53], v[52:53], v[176:177] op_sel_hi:[1,0]
	v_pk_mul_f32 v[50:51], v[50:51], v[176:177] op_sel_hi:[1,0]
	v_pk_mul_f32 v[48:49], v[48:49], v[176:177] op_sel_hi:[1,0]
	v_mul_f32_e32 v172, v172, v176
